# P5b x1 stores without nt (cache policy experiment)
# speedup vs baseline: 1.0002x; 1.0002x over previous
; __device__ __forceinline__ float bf_lo(unsigned w) { return __uint_as_float(w << 16); }
; __device__ __forceinline__ float bf_hi(unsigned w) { return __uint_as_float(w & 0xffff0000u); }
; #define INP(i) ((const float*)(const GAS float*)KARG(8 * (i)))
; #define X_IN INP(0)
; __global__ void __launch_bounds__(512, 2) fwd(Params P) {
;     ...
;     if (PHASE_MASK & (1 << 6)) {
;         const f32x4* g1 = (const f32x4*)INP(12) + lane; const f32x4* g2 = (const f32x4*)INP(13) + lane;
;         for (int m = gw; m < T_TOK; m += NGW) {
;             const float rsy = __builtin_amdgcn_rsqf(ssq_y[m] * (1.f / DM) + EPS);
;             const f32x4* xr = (const f32x4*)(X_IN + (size_t)m * DM) + lane; const u32x2* yr = (const u32x2*)(YB + (size_t)m * DM) + lane;
;             f32x4* orow = (f32x4*)(OUT_P + (size_t)m * DM) + lane;
;             f32x4 v[8]; float s = 0.f;
; #pragma unroll
;             for (int j = 0; j < 8; ++j) { const f32x4 xv = __builtin_nontemporal_load(&xr[64 * j]); const u32x2 yw = __builtin_nontemporal_load(&yr[64 * j]); const f32x4 g = g1[64 * j];
;                 f32x4 t; t.x = xv.x + bf_lo(yw.x) * rsy * g.x; t.y = xv.y + bf_hi(yw.x) * rsy * g.y; t.z = xv.z + bf_lo(yw.y) * rsy * g.z; t.w = xv.w + bf_hi(yw.y) * rsy * g.w;
;                 v[j] = t; __builtin_nontemporal_store(t, &orow[64 * j]); s += (t.x * t.x + t.y * t.y) + (t.z * t.z + t.w * t.w); }
.LBB0_1226:
	s_or_b64 exec, exec, s[6:7]
	v_readlane_b32 s12, v246, 4
	v_readlane_b32 s13, v246, 5
	s_mov_b64 s[8:9], s[0:1]
	s_mov_b64 s[10:11], s[0:1]
	s_waitcnt lgkmcnt(0)
	v_cndmask_b32_e64 v0, 0, 1, s[12:13]
	v_cmp_ne_u32_e64 s[6:7], 1, v0
	s_andn2_b64 vcc, exec, s[12:13]
	s_barrier
	s_cbranch_vccnz .LBB0_1229
	s_load_dwordx2 s[8:9], s[0:1], 0x0
	s_load_dwordx2 s[10:11], s[0:1], 0xa8
	s_load_dwordx2 s[18:19], s[0:1], 0xa0
	s_load_dwordx2 s[20:21], s[0:1], 0x8
	s_load_dwordx2 s[24:25], s[0:1], 0x60
	s_load_dwordx2 s[26:27], s[0:1], 0x68
	v_mov_b32_e32 v167, 0
	v_lshlrev_b32_e32 v181, 3, v179
	v_mov_b32_e32 v182, 0x358637bd
	s_mov_b32 s30, s80
	s_waitcnt lgkmcnt(0)
	s_add_u32 s8, s8, 0x1000
	s_addc_u32 s9, s9, 0
	s_add_u32 s18, s18, 0x1000
	s_addc_u32 s19, s19, 0
	s_add_u32 s12, s10, 0x40000
	s_addc_u32 s13, s11, 0
	s_add_u32 s14, s10, 0x18000000
	s_addc_u32 s15, s11, 0
	s_add_u32 s16, s10, 0x8000000
	s_addc_u32 s17, s11, 0
	s_add_u32 s22, s10, 0x30000000
	s_addc_u32 s23, s11, 0
	s_add_u32 s28, s24, 0x1000
	s_addc_u32 s29, s25, 0
	s_add_u32 s34, s26, 0x1000
	s_addc_u32 s35, s27, 0
	global_load_dwordx4 v[0:3], v166, s[24:25] offset:0
	global_load_dwordx4 v[4:7], v166, s[24:25] offset:1024
	global_load_dwordx4 v[8:11], v166, s[24:25] offset:2048
	global_load_dwordx4 v[12:15], v166, s[24:25] offset:3072
	global_load_dwordx4 v[16:19], v166, s[28:29] offset:0
	global_load_dwordx4 v[20:23], v166, s[28:29] offset:1024
	global_load_dwordx4 v[24:27], v166, s[28:29] offset:2048
	global_load_dwordx4 v[28:31], v166, s[28:29] offset:3072
	global_load_dwordx4 v[32:35], v166, s[26:27] offset:0
	global_load_dwordx4 v[36:39], v166, s[26:27] offset:1024
	global_load_dwordx4 v[40:43], v166, s[26:27] offset:2048
	global_load_dwordx4 v[44:47], v166, s[26:27] offset:3072
	global_load_dwordx4 v[48:51], v166, s[34:35] offset:0
	global_load_dwordx4 v[52:55], v166, s[34:35] offset:1024
	global_load_dwordx4 v[56:59], v166, s[34:35] offset:2048
	global_load_dwordx4 v[60:63], v166, s[34:35] offset:3072
	s_lshl_b32 s2, s30, 13
	s_add_u32 s24, s8, s2
	s_addc_u32 s25, s9, 0
	s_lshl_b32 s2, s30, 12
	s_add_u32 s26, s14, s2
	s_addc_u32 s27, s15, 0
	s_lshl_b32 s2, s30, 2
	s_add_u32 s28, s12, s2
	s_addc_u32 s29, s13, 0
	s_lshl_b32 s2, s30, 10
	s_add_u32 s34, s20, s2
	s_addc_u32 s35, s21, 0
	global_load_dword v112, v167, s[28:29]
	global_load_dwordx4 v[64:67], v166, s[24:25] offset:-4096 nt
	global_load_dwordx2 v[96:97], v181, s[26:27] offset:0 nt
	global_load_dwordx4 v[68:71], v166, s[24:25] offset:-3072 nt
	global_load_dwordx2 v[98:99], v181, s[26:27] offset:512 nt
	global_load_dwordx4 v[72:75], v166, s[24:25] offset:-2048 nt
	global_load_dwordx2 v[100:101], v181, s[26:27] offset:1024 nt
	global_load_dwordx4 v[76:79], v166, s[24:25] offset:-1024 nt
	global_load_dwordx2 v[102:103], v181, s[26:27] offset:1536 nt
	global_load_dwordx4 v[80:83], v166, s[24:25] offset:0 nt
	global_load_dwordx2 v[104:105], v181, s[26:27] offset:2048 nt
	global_load_dwordx4 v[84:87], v166, s[24:25] offset:1024 nt
	global_load_dwordx2 v[106:107], v181, s[26:27] offset:2560 nt
	global_load_dwordx4 v[88:91], v166, s[24:25] offset:2048 nt
	global_load_dwordx2 v[108:109], v181, s[26:27] offset:3072 nt
	global_load_dwordx4 v[92:95], v166, s[24:25] offset:3072 nt
	global_load_dwordx2 v[110:111], v181, s[26:27] offset:3584 nt
	global_load_dwordx4 v[114:117], v166, s[34:35]
	s_lshl_b32 s2, s30, 13
	s_add_u32 s36, s18, s2
	s_addc_u32 s37, s19, 0
	s_lshl_b32 s2, s30, 12
	s_add_u32 s38, s16, s2
	s_addc_u32 s39, s17, 0
	s_lshl_b32 s2, s30, 9
	s_add_u32 s40, s22, s2
	s_addc_u32 s41, s23, 0
	s_add_i32 s10, s30, s82
	s_cmpk_gt_i32 s10, 0x7fff
	s_cselect_b32 s10, s30, s10
	s_lshl_b32 s2, s10, 13
	s_add_u32 s24, s8, s2
	s_addc_u32 s25, s9, 0
	s_lshl_b32 s2, s10, 12
	s_add_u32 s26, s14, s2
	s_addc_u32 s27, s15, 0
	s_lshl_b32 s2, s10, 2
	s_add_u32 s28, s12, s2
	s_addc_u32 s29, s13, 0
	s_lshl_b32 s2, s10, 10
	s_add_u32 s34, s20, s2
	s_addc_u32 s35, s21, 0
	global_load_dword v168, v167, s[28:29]
	global_load_dwordx4 v[118:121], v166, s[24:25] offset:-4096 nt
	global_load_dwordx2 v[150:151], v181, s[26:27] offset:0 nt
	global_load_dwordx4 v[122:125], v166, s[24:25] offset:-3072 nt
	global_load_dwordx2 v[152:153], v181, s[26:27] offset:512 nt
	global_load_dwordx4 v[126:129], v166, s[24:25] offset:-2048 nt
	global_load_dwordx2 v[154:155], v181, s[26:27] offset:1024 nt
	global_load_dwordx4 v[130:133], v166, s[24:25] offset:-1024 nt
	global_load_dwordx2 v[156:157], v181, s[26:27] offset:1536 nt
	global_load_dwordx4 v[134:137], v166, s[24:25] offset:0 nt
	global_load_dwordx2 v[158:159], v181, s[26:27] offset:2048 nt
	global_load_dwordx4 v[138:141], v166, s[24:25] offset:1024 nt
	global_load_dwordx2 v[160:161], v181, s[26:27] offset:2560 nt
	global_load_dwordx4 v[142:145], v166, s[24:25] offset:2048 nt
	global_load_dwordx2 v[162:163], v181, s[26:27] offset:3072 nt
	global_load_dwordx4 v[146:149], v166, s[24:25] offset:3072 nt
	global_load_dwordx2 v[164:165], v181, s[26:27] offset:3584 nt
	global_load_dwordx4 v[170:173], v166, s[34:35]
	s_waitcnt vmcnt(33)
	v_fmamk_f32 v183, v112, 0x3a000000, v182
	v_rsq_f32_e32 v183, v183
	v_lshlrev_b32_e32 v174, 16, v96
	v_and_b32_e32 v175, 0xffff0000, v96
	v_lshlrev_b32_e32 v176, 16, v97
	v_and_b32_e32 v177, 0xffff0000, v97
	v_mul_f32_e32 v174, v183, v174
	v_mul_f32_e32 v175, v183, v175
	v_mul_f32_e32 v176, v183, v176
	v_mul_f32_e32 v177, v183, v177
	v_fma_f32 v64, v0, v174, v64
	v_fma_f32 v65, v1, v175, v65
	v_fma_f32 v66, v2, v176, v66
	v_fma_f32 v67, v3, v177, v67
	global_store_dwordx4 v166, v[64:67], s[36:37] offset:-4096
	v_mul_f32_e32 v185, v64, v64
	v_mul_f32_e32 v186, v65, v65
	v_mul_f32_e32 v187, v66, v66
	v_mul_f32_e32 v188, v67, v67
	s_waitcnt vmcnt(32)
; __device__ __forceinline__ unsigned pk2(float lo, float hi) { return pg8::cvt_pk_bf16(lo, hi); }
; __device__ __forceinline__ float bf_lo(unsigned w) { return __uint_as_float(w << 16); }
; __device__ __forceinline__ float bf_hi(unsigned w) { return __uint_as_float(w & 0xffff0000u); }
; __global__ void __launch_bounds__(512, 2) fwd(Params P) {
;     ...
;             for (int j = 0; j < 8; ++j) { const f32x4 xv = __builtin_nontemporal_load(&xr[64 * j]); const u32x2 yw = __builtin_nontemporal_load(&yr[64 * j]); const f32x4 g = g1[64 * j];
;                 f32x4 t; t.x = xv.x + bf_lo(yw.x) * rsy * g.x; t.y = xv.y + bf_hi(yw.x) * rsy * g.y; t.z = xv.z + bf_lo(yw.y) * rsy * g.z; t.w = xv.w + bf_hi(yw.y) * rsy * g.w;
;                 v[j] = t; __builtin_nontemporal_store(t, &orow[64 * j]); s += (t.x * t.x + t.y * t.y) + (t.z * t.z + t.w * t.w); }
;             const float rs = __builtin_amdgcn_rsqf(wave_sum(s) * (1.f / DM) + EPS);
;             u32x2* o = (u32x2*)(XN + (size_t)m * DM) + lane;
; #pragma unroll
;             for (int j = 0; j < 8; ++j) { const f32x4 g = g2[64 * j]; u32x2 w; w.x = pk2(v[j].x * rs * g.x, v[j].y * rs * g.y); w.y = pk2(v[j].z * rs * g.z, v[j].w * rs * g.w); o[64 * j] = w; }
	v_lshlrev_b32_e32 v174, 16, v98
	v_and_b32_e32 v175, 0xffff0000, v98
	v_lshlrev_b32_e32 v176, 16, v99
	v_and_b32_e32 v177, 0xffff0000, v99
	v_mul_f32_e32 v174, v183, v174
	v_mul_f32_e32 v175, v183, v175
	v_mul_f32_e32 v176, v183, v176
	v_mul_f32_e32 v177, v183, v177
	v_fma_f32 v68, v4, v174, v68
	v_fma_f32 v69, v5, v175, v69
	v_fma_f32 v70, v6, v176, v70
	v_fma_f32 v71, v7, v177, v71
	global_store_dwordx4 v166, v[68:71], s[36:37] offset:-3072
	v_fma_f32 v185, v68, v68, v185
	v_fma_f32 v186, v69, v69, v186
	v_fma_f32 v187, v70, v70, v187
	v_fma_f32 v188, v71, v71, v188
	s_waitcnt vmcnt(31)
	v_lshlrev_b32_e32 v174, 16, v100
	v_and_b32_e32 v175, 0xffff0000, v100
	v_lshlrev_b32_e32 v176, 16, v101
	v_and_b32_e32 v177, 0xffff0000, v101
	v_mul_f32_e32 v174, v183, v174
	v_mul_f32_e32 v175, v183, v175
	v_mul_f32_e32 v176, v183, v176
	v_mul_f32_e32 v177, v183, v177
	v_fma_f32 v72, v8, v174, v72
	v_fma_f32 v73, v9, v175, v73
	v_fma_f32 v74, v10, v176, v74
	v_fma_f32 v75, v11, v177, v75
	global_store_dwordx4 v166, v[72:75], s[36:37] offset:-2048
	v_fma_f32 v185, v72, v72, v185
	v_fma_f32 v186, v73, v73, v186
	v_fma_f32 v187, v74, v74, v187
	v_fma_f32 v188, v75, v75, v188
	s_waitcnt vmcnt(30)
	v_lshlrev_b32_e32 v174, 16, v102
	v_and_b32_e32 v175, 0xffff0000, v102
	v_lshlrev_b32_e32 v176, 16, v103
	v_and_b32_e32 v177, 0xffff0000, v103
	v_mul_f32_e32 v174, v183, v174
	v_mul_f32_e32 v175, v183, v175
	v_mul_f32_e32 v176, v183, v176
	v_mul_f32_e32 v177, v183, v177
	v_fma_f32 v76, v12, v174, v76
	v_fma_f32 v77, v13, v175, v77
	v_fma_f32 v78, v14, v176, v78
	v_fma_f32 v79, v15, v177, v79
	global_store_dwordx4 v166, v[76:79], s[36:37] offset:-1024
	v_fma_f32 v185, v76, v76, v185
	v_fma_f32 v186, v77, v77, v186
	v_fma_f32 v187, v78, v78, v187
	v_fma_f32 v188, v79, v79, v188
	s_waitcnt vmcnt(29)
	v_lshlrev_b32_e32 v174, 16, v104
	v_and_b32_e32 v175, 0xffff0000, v104
	v_lshlrev_b32_e32 v176, 16, v105
	v_and_b32_e32 v177, 0xffff0000, v105
	v_mul_f32_e32 v174, v183, v174
	v_mul_f32_e32 v175, v183, v175
	v_mul_f32_e32 v176, v183, v176
	v_mul_f32_e32 v177, v183, v177
	v_fma_f32 v80, v16, v174, v80
	v_fma_f32 v81, v17, v175, v81
	v_fma_f32 v82, v18, v176, v82
	v_fma_f32 v83, v19, v177, v83
	global_store_dwordx4 v166, v[80:83], s[36:37] offset:0
	v_fma_f32 v185, v80, v80, v185
	v_fma_f32 v186, v81, v81, v186
	v_fma_f32 v187, v82, v82, v187
	v_fma_f32 v188, v83, v83, v188
	s_waitcnt vmcnt(28)
	v_lshlrev_b32_e32 v174, 16, v106
	v_and_b32_e32 v175, 0xffff0000, v106
	v_lshlrev_b32_e32 v176, 16, v107
	v_and_b32_e32 v177, 0xffff0000, v107
	v_mul_f32_e32 v174, v183, v174
	v_mul_f32_e32 v175, v183, v175
	v_mul_f32_e32 v176, v183, v176
	v_mul_f32_e32 v177, v183, v177
	v_fma_f32 v84, v20, v174, v84
	v_fma_f32 v85, v21, v175, v85
	v_fma_f32 v86, v22, v176, v86
	v_fma_f32 v87, v23, v177, v87
	global_store_dwordx4 v166, v[84:87], s[36:37] offset:1024
	v_fma_f32 v185, v84, v84, v185
	v_fma_f32 v186, v85, v85, v186
	v_fma_f32 v187, v86, v86, v187
	v_fma_f32 v188, v87, v87, v188
	s_waitcnt vmcnt(27)
	v_lshlrev_b32_e32 v174, 16, v108
	v_and_b32_e32 v175, 0xffff0000, v108
	v_lshlrev_b32_e32 v176, 16, v109
	v_and_b32_e32 v177, 0xffff0000, v109
	v_mul_f32_e32 v174, v183, v174
	v_mul_f32_e32 v175, v183, v175
	v_mul_f32_e32 v176, v183, v176
	v_mul_f32_e32 v177, v183, v177
	v_fma_f32 v88, v24, v174, v88
	v_fma_f32 v89, v25, v175, v89
	v_fma_f32 v90, v26, v176, v90
	v_fma_f32 v91, v27, v177, v91
	global_store_dwordx4 v166, v[88:91], s[36:37] offset:2048
	v_fma_f32 v185, v88, v88, v185
	v_fma_f32 v186, v89, v89, v186
	v_fma_f32 v187, v90, v90, v187
	v_fma_f32 v188, v91, v91, v188
	s_waitcnt vmcnt(26)
	v_lshlrev_b32_e32 v174, 16, v110
	v_and_b32_e32 v175, 0xffff0000, v110
	v_lshlrev_b32_e32 v176, 16, v111
	v_and_b32_e32 v177, 0xffff0000, v111
	v_mul_f32_e32 v174, v183, v174
	v_mul_f32_e32 v175, v183, v175
	v_mul_f32_e32 v176, v183, v176
	v_mul_f32_e32 v177, v183, v177
	v_fma_f32 v92, v28, v174, v92
	v_fma_f32 v93, v29, v175, v93
	v_fma_f32 v94, v30, v176, v94
	v_fma_f32 v95, v31, v177, v95
	global_store_dwordx4 v166, v[92:95], s[36:37] offset:3072
	v_fma_f32 v185, v92, v92, v185
	v_fma_f32 v186, v93, v93, v186
	v_fma_f32 v187, v94, v94, v187
	v_fma_f32 v188, v95, v95, v188
	v_add_f32_e32 v185, v185, v186
	v_add_f32_e32 v187, v187, v188
	v_add_f32_e32 v185, v185, v187
	s_nop 1
	v_add_f32_dpp v185, v185, v185 quad_perm:[1,0,3,2] row_mask:0xf bank_mask:0xf
	s_nop 1
	v_add_f32_dpp v185, v185, v185 quad_perm:[2,3,0,1] row_mask:0xf bank_mask:0xf
	s_nop 1
	v_add_f32_dpp v185, v185, v185 row_half_mirror row_mask:0xf bank_mask:0xf
	s_nop 1
	v_add_f32_dpp v185, v185, v185 row_mirror row_mask:0xf bank_mask:0xf
	s_nop 1
	v_readlane_b32 s24, v185, 0
	v_readlane_b32 s25, v185, 16
	v_readlane_b32 s26, v185, 32
	v_readlane_b32 s27, v185, 48
	v_mov_b32_e32 v184, s24
	v_add_f32_e32 v184, s25, v184
	v_add_f32_e32 v184, s26, v184
	v_add_f32_e32 v184, s27, v184
	v_fmamk_f32 v184, v184, 0x3a000000, v182
	v_rsq_f32_e32 v184, v184
	s_nop 0
	v_mul_f32_e32 v174, v184, v64
	v_mul_f32_e32 v175, v184, v65
	v_mul_f32_e32 v176, v184, v66
	v_mul_f32_e32 v177, v184, v67
	v_mul_f32_e32 v174, v174, v32
	v_mul_f32_e32 v175, v175, v33
	v_mul_f32_e32 v176, v176, v34
	v_mul_f32_e32 v177, v177, v35
	v_cvt_pk_bf16_f32 v96, v174, v175
	v_cvt_pk_bf16_f32 v97, v176, v177
	global_store_dwordx2 v181, v[96:97], s[38:39] offset:0
	v_mul_f32_e32 v174, v184, v68
	v_mul_f32_e32 v175, v184, v69
	v_mul_f32_e32 v176, v184, v70
	v_mul_f32_e32 v177, v184, v71
	v_mul_f32_e32 v174, v174, v36
	v_mul_f32_e32 v175, v175, v37
	v_mul_f32_e32 v176, v176, v38
	v_mul_f32_e32 v177, v177, v39
	v_cvt_pk_bf16_f32 v98, v174, v175
	v_cvt_pk_bf16_f32 v99, v176, v177
; __device__ __forceinline__ unsigned pk2(float lo, float hi) { return pg8::cvt_pk_bf16(lo, hi); }
; __device__ __forceinline__ float bf_lo(unsigned w) { return __uint_as_float(w << 16); }
; __device__ __forceinline__ float bf_hi(unsigned w) { return __uint_as_float(w & 0xffff0000u); }
; #define X_IN INP(0)
; #define P_IN INP(1)
; __global__ void __launch_bounds__(512, 2) fwd(Params P) {
;     ...
;         for (int m = gw; m < T_TOK; m += NGW) {
;             const float rsy = __builtin_amdgcn_rsqf(ssq_y[m] * (1.f / DM) + EPS);
;             const f32x4* xr = (const f32x4*)(X_IN + (size_t)m * DM) + lane; const u32x2* yr = (const u32x2*)(YB + (size_t)m * DM) + lane;
;             f32x4* orow = (f32x4*)(OUT_P + (size_t)m * DM) + lane;
;             f32x4 v[8]; float s = 0.f;
; #pragma unroll
;             for (int j = 0; j < 8; ++j) { const f32x4 xv = __builtin_nontemporal_load(&xr[64 * j]); const u32x2 yw = __builtin_nontemporal_load(&yr[64 * j]); const f32x4 g = g1[64 * j];
;                 f32x4 t; t.x = xv.x + bf_lo(yw.x) * rsy * g.x; t.y = xv.y + bf_hi(yw.x) * rsy * g.y; t.z = xv.z + bf_lo(yw.y) * rsy * g.z; t.w = xv.w + bf_hi(yw.y) * rsy * g.w;
;                 v[j] = t; __builtin_nontemporal_store(t, &orow[64 * j]); s += (t.x * t.x + t.y * t.y) + (t.z * t.z + t.w * t.w); }
;     ...
;             u32x2* o = (u32x2*)(XN + (size_t)m * DM) + lane;
; #pragma unroll
;             for (int j = 0; j < 8; ++j) { const f32x4 g = g2[64 * j]; u32x2 w; w.x = pk2(v[j].x * rs * g.x, v[j].y * rs * g.y); w.y = pk2(v[j].z * rs * g.z, v[j].w * rs * g.w); o[64 * j] = w; }
;             const f32x4 pv = ((const f32x4*)(P_IN + (size_t)m * PLE))[lane]; u32x2 pw; pw.x = pk2(pv.x, pv.y); pw.y = pk2(pv.z, pv.w);
;             ((u32x2*)(PB + (size_t)m * PLE))[lane] = pw;
	global_store_dwordx2 v181, v[98:99], s[38:39] offset:512
	v_mul_f32_e32 v174, v184, v72
	v_mul_f32_e32 v175, v184, v73
	v_mul_f32_e32 v176, v184, v74
	v_mul_f32_e32 v177, v184, v75
	v_mul_f32_e32 v174, v174, v40
	v_mul_f32_e32 v175, v175, v41
	v_mul_f32_e32 v176, v176, v42
	v_mul_f32_e32 v177, v177, v43
	v_cvt_pk_bf16_f32 v100, v174, v175
	v_cvt_pk_bf16_f32 v101, v176, v177
	global_store_dwordx2 v181, v[100:101], s[38:39] offset:1024
	v_mul_f32_e32 v174, v184, v76
	v_mul_f32_e32 v175, v184, v77
	v_mul_f32_e32 v176, v184, v78
	v_mul_f32_e32 v177, v184, v79
	v_mul_f32_e32 v174, v174, v44
	v_mul_f32_e32 v175, v175, v45
	v_mul_f32_e32 v176, v176, v46
	v_mul_f32_e32 v177, v177, v47
	v_cvt_pk_bf16_f32 v102, v174, v175
	v_cvt_pk_bf16_f32 v103, v176, v177
	global_store_dwordx2 v181, v[102:103], s[38:39] offset:1536
	v_mul_f32_e32 v174, v184, v80
	v_mul_f32_e32 v175, v184, v81
	v_mul_f32_e32 v176, v184, v82
	v_mul_f32_e32 v177, v184, v83
	v_mul_f32_e32 v174, v174, v48
	v_mul_f32_e32 v175, v175, v49
	v_mul_f32_e32 v176, v176, v50
	v_mul_f32_e32 v177, v177, v51
	v_cvt_pk_bf16_f32 v104, v174, v175
	v_cvt_pk_bf16_f32 v105, v176, v177
	global_store_dwordx2 v181, v[104:105], s[38:39] offset:2048
	v_mul_f32_e32 v174, v184, v84
	v_mul_f32_e32 v175, v184, v85
	v_mul_f32_e32 v176, v184, v86
	v_mul_f32_e32 v177, v184, v87
	v_mul_f32_e32 v174, v174, v52
	v_mul_f32_e32 v175, v175, v53
	v_mul_f32_e32 v176, v176, v54
	v_mul_f32_e32 v177, v177, v55
	v_cvt_pk_bf16_f32 v106, v174, v175
	v_cvt_pk_bf16_f32 v107, v176, v177
	global_store_dwordx2 v181, v[106:107], s[38:39] offset:2560
	v_mul_f32_e32 v174, v184, v88
	v_mul_f32_e32 v175, v184, v89
	v_mul_f32_e32 v176, v184, v90
	v_mul_f32_e32 v177, v184, v91
	v_mul_f32_e32 v174, v174, v56
	v_mul_f32_e32 v175, v175, v57
	v_mul_f32_e32 v176, v176, v58
	v_mul_f32_e32 v177, v177, v59
	v_cvt_pk_bf16_f32 v108, v174, v175
	v_cvt_pk_bf16_f32 v109, v176, v177
	global_store_dwordx2 v181, v[108:109], s[38:39] offset:3072
	v_mul_f32_e32 v174, v184, v92
	v_mul_f32_e32 v175, v184, v93
	v_mul_f32_e32 v176, v184, v94
	v_mul_f32_e32 v177, v184, v95
	v_mul_f32_e32 v174, v174, v60
	v_mul_f32_e32 v175, v175, v61
	v_mul_f32_e32 v176, v176, v62
	v_mul_f32_e32 v177, v177, v63
	v_cvt_pk_bf16_f32 v110, v174, v175
	v_cvt_pk_bf16_f32 v111, v176, v177
	global_store_dwordx2 v181, v[110:111], s[38:39] offset:3584
	s_waitcnt vmcnt(34)
	v_cvt_pk_bf16_f32 v114, v114, v115
	v_cvt_pk_bf16_f32 v115, v116, v117
	global_store_dwordx2 v181, v[114:115], s[40:41]
	s_add_i32 s30, s30, s82
	s_cmpk_gt_i32 s30, 0x7fff
	s_cbranch_scc1 .Lp5b_done
.Lp5b_loop:
	s_lshl_b32 s2, s30, 13
	s_add_u32 s36, s18, s2
	s_addc_u32 s37, s19, 0
	s_lshl_b32 s2, s30, 12
	s_add_u32 s38, s16, s2
	s_addc_u32 s39, s17, 0
	s_lshl_b32 s2, s30, 9
	s_add_u32 s40, s22, s2
	s_addc_u32 s41, s23, 0
	s_add_i32 s10, s30, s82
	s_cmpk_gt_i32 s10, 0x7fff
	s_cselect_b32 s10, s30, s10
	s_lshl_b32 s2, s10, 13
	s_add_u32 s24, s8, s2
	s_addc_u32 s25, s9, 0
	s_lshl_b32 s2, s10, 12
	s_add_u32 s26, s14, s2
	s_addc_u32 s27, s15, 0
	s_lshl_b32 s2, s10, 2
	s_add_u32 s28, s12, s2
	s_addc_u32 s29, s13, 0
	s_lshl_b32 s2, s10, 10
	s_add_u32 s34, s20, s2
	s_addc_u32 s35, s21, 0
	global_load_dword v112, v167, s[28:29]
	global_load_dwordx4 v[64:67], v166, s[24:25] offset:-4096 nt
	global_load_dwordx2 v[96:97], v181, s[26:27] offset:0 nt
	global_load_dwordx4 v[68:71], v166, s[24:25] offset:-3072 nt
	global_load_dwordx2 v[98:99], v181, s[26:27] offset:512 nt
	global_load_dwordx4 v[72:75], v166, s[24:25] offset:-2048 nt
	global_load_dwordx2 v[100:101], v181, s[26:27] offset:1024 nt
	global_load_dwordx4 v[76:79], v166, s[24:25] offset:-1024 nt
	global_load_dwordx2 v[102:103], v181, s[26:27] offset:1536 nt
	global_load_dwordx4 v[80:83], v166, s[24:25] offset:0 nt
	global_load_dwordx2 v[104:105], v181, s[26:27] offset:2048 nt
	global_load_dwordx4 v[84:87], v166, s[24:25] offset:1024 nt
	global_load_dwordx2 v[106:107], v181, s[26:27] offset:2560 nt
	global_load_dwordx4 v[88:91], v166, s[24:25] offset:2048 nt
	global_load_dwordx2 v[108:109], v181, s[26:27] offset:3072 nt
	global_load_dwordx4 v[92:95], v166, s[24:25] offset:3072 nt
	global_load_dwordx2 v[110:111], v181, s[26:27] offset:3584 nt
	global_load_dwordx4 v[114:117], v166, s[34:35]
	s_waitcnt vmcnt(50)
	v_fmamk_f32 v183, v168, 0x3a000000, v182
	v_rsq_f32_e32 v183, v183
	v_lshlrev_b32_e32 v174, 16, v150
	v_and_b32_e32 v175, 0xffff0000, v150
	v_lshlrev_b32_e32 v176, 16, v151
	v_and_b32_e32 v177, 0xffff0000, v151
	v_mul_f32_e32 v174, v183, v174
	v_mul_f32_e32 v175, v183, v175
	v_mul_f32_e32 v176, v183, v176
	v_mul_f32_e32 v177, v183, v177
	v_fma_f32 v118, v0, v174, v118
	v_fma_f32 v119, v1, v175, v119
	v_fma_f32 v120, v2, v176, v120
	v_fma_f32 v121, v3, v177, v121
	global_store_dwordx4 v166, v[118:121], s[36:37] offset:-4096
	v_mul_f32_e32 v185, v118, v118
	v_mul_f32_e32 v186, v119, v119
	v_mul_f32_e32 v187, v120, v120
	v_mul_f32_e32 v188, v121, v121
	s_waitcnt vmcnt(49)
	v_lshlrev_b32_e32 v174, 16, v152
	v_and_b32_e32 v175, 0xffff0000, v152
	v_lshlrev_b32_e32 v176, 16, v153
	v_and_b32_e32 v177, 0xffff0000, v153
	v_mul_f32_e32 v174, v183, v174
	v_mul_f32_e32 v175, v183, v175
	v_mul_f32_e32 v176, v183, v176
	v_mul_f32_e32 v177, v183, v177
	v_fma_f32 v122, v4, v174, v122
	v_fma_f32 v123, v5, v175, v123
	v_fma_f32 v124, v6, v176, v124
	v_fma_f32 v125, v7, v177, v125
	global_store_dwordx4 v166, v[122:125], s[36:37] offset:-3072
	v_fma_f32 v185, v122, v122, v185
	v_fma_f32 v186, v123, v123, v186
	v_fma_f32 v187, v124, v124, v187
	v_fma_f32 v188, v125, v125, v188
	s_waitcnt vmcnt(48)
; __device__ __forceinline__ unsigned pk2(float lo, float hi) { return pg8::cvt_pk_bf16(lo, hi); }
; __device__ __forceinline__ float bf_lo(unsigned w) { return __uint_as_float(w << 16); }
; __device__ __forceinline__ float bf_hi(unsigned w) { return __uint_as_float(w & 0xffff0000u); }
; __global__ void __launch_bounds__(512, 2) fwd(Params P) {
;     ...
;             for (int j = 0; j < 8; ++j) { const f32x4 xv = __builtin_nontemporal_load(&xr[64 * j]); const u32x2 yw = __builtin_nontemporal_load(&yr[64 * j]); const f32x4 g = g1[64 * j];
;                 f32x4 t; t.x = xv.x + bf_lo(yw.x) * rsy * g.x; t.y = xv.y + bf_hi(yw.x) * rsy * g.y; t.z = xv.z + bf_lo(yw.y) * rsy * g.z; t.w = xv.w + bf_hi(yw.y) * rsy * g.w;
;                 v[j] = t; __builtin_nontemporal_store(t, &orow[64 * j]); s += (t.x * t.x + t.y * t.y) + (t.z * t.z + t.w * t.w); }
;             const float rs = __builtin_amdgcn_rsqf(wave_sum(s) * (1.f / DM) + EPS);
;             u32x2* o = (u32x2*)(XN + (size_t)m * DM) + lane;
; #pragma unroll
;             for (int j = 0; j < 8; ++j) { const f32x4 g = g2[64 * j]; u32x2 w; w.x = pk2(v[j].x * rs * g.x, v[j].y * rs * g.y); w.y = pk2(v[j].z * rs * g.z, v[j].w * rs * g.w); o[64 * j] = w; }
	v_lshlrev_b32_e32 v174, 16, v154
	v_and_b32_e32 v175, 0xffff0000, v154
	v_lshlrev_b32_e32 v176, 16, v155
	v_and_b32_e32 v177, 0xffff0000, v155
	v_mul_f32_e32 v174, v183, v174
	v_mul_f32_e32 v175, v183, v175
	v_mul_f32_e32 v176, v183, v176
	v_mul_f32_e32 v177, v183, v177
	v_fma_f32 v126, v8, v174, v126
	v_fma_f32 v127, v9, v175, v127
	v_fma_f32 v128, v10, v176, v128
	v_fma_f32 v129, v11, v177, v129
	global_store_dwordx4 v166, v[126:129], s[36:37] offset:-2048
	v_fma_f32 v185, v126, v126, v185
	v_fma_f32 v186, v127, v127, v186
	v_fma_f32 v187, v128, v128, v187
	v_fma_f32 v188, v129, v129, v188
	s_waitcnt vmcnt(47)
	v_lshlrev_b32_e32 v174, 16, v156
	v_and_b32_e32 v175, 0xffff0000, v156
	v_lshlrev_b32_e32 v176, 16, v157
	v_and_b32_e32 v177, 0xffff0000, v157
	v_mul_f32_e32 v174, v183, v174
	v_mul_f32_e32 v175, v183, v175
	v_mul_f32_e32 v176, v183, v176
	v_mul_f32_e32 v177, v183, v177
	v_fma_f32 v130, v12, v174, v130
	v_fma_f32 v131, v13, v175, v131
	v_fma_f32 v132, v14, v176, v132
	v_fma_f32 v133, v15, v177, v133
	global_store_dwordx4 v166, v[130:133], s[36:37] offset:-1024
	v_fma_f32 v185, v130, v130, v185
	v_fma_f32 v186, v131, v131, v186
	v_fma_f32 v187, v132, v132, v187
	v_fma_f32 v188, v133, v133, v188
	s_waitcnt vmcnt(46)
	v_lshlrev_b32_e32 v174, 16, v158
	v_and_b32_e32 v175, 0xffff0000, v158
	v_lshlrev_b32_e32 v176, 16, v159
	v_and_b32_e32 v177, 0xffff0000, v159
	v_mul_f32_e32 v174, v183, v174
	v_mul_f32_e32 v175, v183, v175
	v_mul_f32_e32 v176, v183, v176
	v_mul_f32_e32 v177, v183, v177
	v_fma_f32 v134, v16, v174, v134
	v_fma_f32 v135, v17, v175, v135
	v_fma_f32 v136, v18, v176, v136
	v_fma_f32 v137, v19, v177, v137
	global_store_dwordx4 v166, v[134:137], s[36:37] offset:0
	v_fma_f32 v185, v134, v134, v185
	v_fma_f32 v186, v135, v135, v186
	v_fma_f32 v187, v136, v136, v187
	v_fma_f32 v188, v137, v137, v188
	s_waitcnt vmcnt(45)
	v_lshlrev_b32_e32 v174, 16, v160
	v_and_b32_e32 v175, 0xffff0000, v160
	v_lshlrev_b32_e32 v176, 16, v161
	v_and_b32_e32 v177, 0xffff0000, v161
	v_mul_f32_e32 v174, v183, v174
	v_mul_f32_e32 v175, v183, v175
	v_mul_f32_e32 v176, v183, v176
	v_mul_f32_e32 v177, v183, v177
	v_fma_f32 v138, v20, v174, v138
	v_fma_f32 v139, v21, v175, v139
	v_fma_f32 v140, v22, v176, v140
	v_fma_f32 v141, v23, v177, v141
	global_store_dwordx4 v166, v[138:141], s[36:37] offset:1024
	v_fma_f32 v185, v138, v138, v185
	v_fma_f32 v186, v139, v139, v186
	v_fma_f32 v187, v140, v140, v187
	v_fma_f32 v188, v141, v141, v188
	s_waitcnt vmcnt(44)
	v_lshlrev_b32_e32 v174, 16, v162
	v_and_b32_e32 v175, 0xffff0000, v162
	v_lshlrev_b32_e32 v176, 16, v163
	v_and_b32_e32 v177, 0xffff0000, v163
	v_mul_f32_e32 v174, v183, v174
	v_mul_f32_e32 v175, v183, v175
	v_mul_f32_e32 v176, v183, v176
	v_mul_f32_e32 v177, v183, v177
	v_fma_f32 v142, v24, v174, v142
	v_fma_f32 v143, v25, v175, v143
	v_fma_f32 v144, v26, v176, v144
	v_fma_f32 v145, v27, v177, v145
	global_store_dwordx4 v166, v[142:145], s[36:37] offset:2048
	v_fma_f32 v185, v142, v142, v185
	v_fma_f32 v186, v143, v143, v186
	v_fma_f32 v187, v144, v144, v187
	v_fma_f32 v188, v145, v145, v188
	s_waitcnt vmcnt(43)
	v_lshlrev_b32_e32 v174, 16, v164
	v_and_b32_e32 v175, 0xffff0000, v164
	v_lshlrev_b32_e32 v176, 16, v165
	v_and_b32_e32 v177, 0xffff0000, v165
	v_mul_f32_e32 v174, v183, v174
	v_mul_f32_e32 v175, v183, v175
	v_mul_f32_e32 v176, v183, v176
	v_mul_f32_e32 v177, v183, v177
	v_fma_f32 v146, v28, v174, v146
	v_fma_f32 v147, v29, v175, v147
	v_fma_f32 v148, v30, v176, v148
	v_fma_f32 v149, v31, v177, v149
	global_store_dwordx4 v166, v[146:149], s[36:37] offset:3072
	v_fma_f32 v185, v146, v146, v185
	v_fma_f32 v186, v147, v147, v186
	v_fma_f32 v187, v148, v148, v187
	v_fma_f32 v188, v149, v149, v188
	v_add_f32_e32 v185, v185, v186
	v_add_f32_e32 v187, v187, v188
	v_add_f32_e32 v185, v185, v187
	s_nop 1
	v_add_f32_dpp v185, v185, v185 quad_perm:[1,0,3,2] row_mask:0xf bank_mask:0xf
	s_nop 1
	v_add_f32_dpp v185, v185, v185 quad_perm:[2,3,0,1] row_mask:0xf bank_mask:0xf
	s_nop 1
	v_add_f32_dpp v185, v185, v185 row_half_mirror row_mask:0xf bank_mask:0xf
	s_nop 1
	v_add_f32_dpp v185, v185, v185 row_mirror row_mask:0xf bank_mask:0xf
	s_nop 1
	v_readlane_b32 s24, v185, 0
	v_readlane_b32 s25, v185, 16
	v_readlane_b32 s26, v185, 32
	v_readlane_b32 s27, v185, 48
	v_mov_b32_e32 v184, s24
	v_add_f32_e32 v184, s25, v184
	v_add_f32_e32 v184, s26, v184
	v_add_f32_e32 v184, s27, v184
	v_fmamk_f32 v184, v184, 0x3a000000, v182
	v_rsq_f32_e32 v184, v184
	s_nop 0
	v_mul_f32_e32 v174, v184, v118
	v_mul_f32_e32 v175, v184, v119
	v_mul_f32_e32 v176, v184, v120
	v_mul_f32_e32 v177, v184, v121
	v_mul_f32_e32 v174, v174, v32
	v_mul_f32_e32 v175, v175, v33
	v_mul_f32_e32 v176, v176, v34
	v_mul_f32_e32 v177, v177, v35
	v_cvt_pk_bf16_f32 v150, v174, v175
	v_cvt_pk_bf16_f32 v151, v176, v177
	global_store_dwordx2 v181, v[150:151], s[38:39] offset:0
	v_mul_f32_e32 v174, v184, v122
	v_mul_f32_e32 v175, v184, v123
	v_mul_f32_e32 v176, v184, v124
	v_mul_f32_e32 v177, v184, v125
	v_mul_f32_e32 v174, v174, v36
	v_mul_f32_e32 v175, v175, v37
	v_mul_f32_e32 v176, v176, v38
	v_mul_f32_e32 v177, v177, v39
	v_cvt_pk_bf16_f32 v152, v174, v175
	v_cvt_pk_bf16_f32 v153, v176, v177
	global_store_dwordx2 v181, v[152:153], s[38:39] offset:512
	v_mul_f32_e32 v174, v184, v126
	v_mul_f32_e32 v175, v184, v127
	v_mul_f32_e32 v176, v184, v128
	v_mul_f32_e32 v177, v184, v129
	v_mul_f32_e32 v174, v174, v40
	v_mul_f32_e32 v175, v175, v41
	v_mul_f32_e32 v176, v176, v42
	v_mul_f32_e32 v177, v177, v43
	v_cvt_pk_bf16_f32 v154, v174, v175
	v_cvt_pk_bf16_f32 v155, v176, v177
	global_store_dwordx2 v181, v[154:155], s[38:39] offset:1024
	v_mul_f32_e32 v174, v184, v130
; __device__ __forceinline__ unsigned pk2(float lo, float hi) { return pg8::cvt_pk_bf16(lo, hi); }
; __device__ __forceinline__ float bf_lo(unsigned w) { return __uint_as_float(w << 16); }
; __device__ __forceinline__ float bf_hi(unsigned w) { return __uint_as_float(w & 0xffff0000u); }
; #define X_IN INP(0)
; #define P_IN INP(1)
; __global__ void __launch_bounds__(512, 2) fwd(Params P) {
;     ...
;         for (int m = gw; m < T_TOK; m += NGW) {
;             const float rsy = __builtin_amdgcn_rsqf(ssq_y[m] * (1.f / DM) + EPS);
;             const f32x4* xr = (const f32x4*)(X_IN + (size_t)m * DM) + lane; const u32x2* yr = (const u32x2*)(YB + (size_t)m * DM) + lane;
;             f32x4* orow = (f32x4*)(OUT_P + (size_t)m * DM) + lane;
;             f32x4 v[8]; float s = 0.f;
; #pragma unroll
;             for (int j = 0; j < 8; ++j) { const f32x4 xv = __builtin_nontemporal_load(&xr[64 * j]); const u32x2 yw = __builtin_nontemporal_load(&yr[64 * j]); const f32x4 g = g1[64 * j];
;                 f32x4 t; t.x = xv.x + bf_lo(yw.x) * rsy * g.x; t.y = xv.y + bf_hi(yw.x) * rsy * g.y; t.z = xv.z + bf_lo(yw.y) * rsy * g.z; t.w = xv.w + bf_hi(yw.y) * rsy * g.w;
;                 v[j] = t; __builtin_nontemporal_store(t, &orow[64 * j]); s += (t.x * t.x + t.y * t.y) + (t.z * t.z + t.w * t.w); }
;     ...
;             u32x2* o = (u32x2*)(XN + (size_t)m * DM) + lane;
; #pragma unroll
;             for (int j = 0; j < 8; ++j) { const f32x4 g = g2[64 * j]; u32x2 w; w.x = pk2(v[j].x * rs * g.x, v[j].y * rs * g.y); w.y = pk2(v[j].z * rs * g.z, v[j].w * rs * g.w); o[64 * j] = w; }
;             const f32x4 pv = ((const f32x4*)(P_IN + (size_t)m * PLE))[lane]; u32x2 pw; pw.x = pk2(pv.x, pv.y); pw.y = pk2(pv.z, pv.w);
;             ((u32x2*)(PB + (size_t)m * PLE))[lane] = pw;
	v_mul_f32_e32 v175, v184, v131
	v_mul_f32_e32 v176, v184, v132
	v_mul_f32_e32 v177, v184, v133
	v_mul_f32_e32 v174, v174, v44
	v_mul_f32_e32 v175, v175, v45
	v_mul_f32_e32 v176, v176, v46
	v_mul_f32_e32 v177, v177, v47
	v_cvt_pk_bf16_f32 v156, v174, v175
	v_cvt_pk_bf16_f32 v157, v176, v177
	global_store_dwordx2 v181, v[156:157], s[38:39] offset:1536
	v_mul_f32_e32 v174, v184, v134
	v_mul_f32_e32 v175, v184, v135
	v_mul_f32_e32 v176, v184, v136
	v_mul_f32_e32 v177, v184, v137
	v_mul_f32_e32 v174, v174, v48
	v_mul_f32_e32 v175, v175, v49
	v_mul_f32_e32 v176, v176, v50
	v_mul_f32_e32 v177, v177, v51
	v_cvt_pk_bf16_f32 v158, v174, v175
	v_cvt_pk_bf16_f32 v159, v176, v177
	global_store_dwordx2 v181, v[158:159], s[38:39] offset:2048
	v_mul_f32_e32 v174, v184, v138
	v_mul_f32_e32 v175, v184, v139
	v_mul_f32_e32 v176, v184, v140
	v_mul_f32_e32 v177, v184, v141
	v_mul_f32_e32 v174, v174, v52
	v_mul_f32_e32 v175, v175, v53
	v_mul_f32_e32 v176, v176, v54
	v_mul_f32_e32 v177, v177, v55
	v_cvt_pk_bf16_f32 v160, v174, v175
	v_cvt_pk_bf16_f32 v161, v176, v177
	global_store_dwordx2 v181, v[160:161], s[38:39] offset:2560
	v_mul_f32_e32 v174, v184, v142
	v_mul_f32_e32 v175, v184, v143
	v_mul_f32_e32 v176, v184, v144
	v_mul_f32_e32 v177, v184, v145
	v_mul_f32_e32 v174, v174, v56
	v_mul_f32_e32 v175, v175, v57
	v_mul_f32_e32 v176, v176, v58
	v_mul_f32_e32 v177, v177, v59
	v_cvt_pk_bf16_f32 v162, v174, v175
	v_cvt_pk_bf16_f32 v163, v176, v177
	global_store_dwordx2 v181, v[162:163], s[38:39] offset:3072
	v_mul_f32_e32 v174, v184, v146
	v_mul_f32_e32 v175, v184, v147
	v_mul_f32_e32 v176, v184, v148
	v_mul_f32_e32 v177, v184, v149
	v_mul_f32_e32 v174, v174, v60
	v_mul_f32_e32 v175, v175, v61
	v_mul_f32_e32 v176, v176, v62
	v_mul_f32_e32 v177, v177, v63
	v_cvt_pk_bf16_f32 v164, v174, v175
	v_cvt_pk_bf16_f32 v165, v176, v177
	global_store_dwordx2 v181, v[164:165], s[38:39] offset:3584
	s_waitcnt vmcnt(51)
	v_cvt_pk_bf16_f32 v170, v170, v171
	v_cvt_pk_bf16_f32 v171, v172, v173
	global_store_dwordx2 v181, v[170:171], s[40:41]
	s_add_i32 s30, s30, s82
	s_cmpk_gt_i32 s30, 0x7fff
	s_cbranch_scc1 .Lp5b_done
	s_lshl_b32 s2, s30, 13
	s_add_u32 s36, s18, s2
	s_addc_u32 s37, s19, 0
	s_lshl_b32 s2, s30, 12
	s_add_u32 s38, s16, s2
	s_addc_u32 s39, s17, 0
	s_lshl_b32 s2, s30, 9
	s_add_u32 s40, s22, s2
	s_addc_u32 s41, s23, 0
	s_add_i32 s10, s30, s82
	s_cmpk_gt_i32 s10, 0x7fff
	s_cselect_b32 s10, s30, s10
	s_lshl_b32 s2, s10, 13
	s_add_u32 s24, s8, s2
	s_addc_u32 s25, s9, 0
	s_lshl_b32 s2, s10, 12
	s_add_u32 s26, s14, s2
	s_addc_u32 s27, s15, 0
	s_lshl_b32 s2, s10, 2
	s_add_u32 s28, s12, s2
	s_addc_u32 s29, s13, 0
	s_lshl_b32 s2, s10, 10
	s_add_u32 s34, s20, s2
	s_addc_u32 s35, s21, 0
	global_load_dword v168, v167, s[28:29]
	global_load_dwordx4 v[118:121], v166, s[24:25] offset:-4096 nt
	global_load_dwordx2 v[150:151], v181, s[26:27] offset:0 nt
	global_load_dwordx4 v[122:125], v166, s[24:25] offset:-3072 nt
	global_load_dwordx2 v[152:153], v181, s[26:27] offset:512 nt
	global_load_dwordx4 v[126:129], v166, s[24:25] offset:-2048 nt
	global_load_dwordx2 v[154:155], v181, s[26:27] offset:1024 nt
	global_load_dwordx4 v[130:133], v166, s[24:25] offset:-1024 nt
	global_load_dwordx2 v[156:157], v181, s[26:27] offset:1536 nt
	global_load_dwordx4 v[134:137], v166, s[24:25] offset:0 nt
	global_load_dwordx2 v[158:159], v181, s[26:27] offset:2048 nt
	global_load_dwordx4 v[138:141], v166, s[24:25] offset:1024 nt
	global_load_dwordx2 v[160:161], v181, s[26:27] offset:2560 nt
	global_load_dwordx4 v[142:145], v166, s[24:25] offset:2048 nt
	global_load_dwordx2 v[162:163], v181, s[26:27] offset:3072 nt
	global_load_dwordx4 v[146:149], v166, s[24:25] offset:3072 nt
	global_load_dwordx2 v[164:165], v181, s[26:27] offset:3584 nt
	global_load_dwordx4 v[170:173], v166, s[34:35]
	s_waitcnt vmcnt(50)
	v_fmamk_f32 v183, v112, 0x3a000000, v182
	v_rsq_f32_e32 v183, v183
	v_lshlrev_b32_e32 v174, 16, v96
	v_and_b32_e32 v175, 0xffff0000, v96
	v_lshlrev_b32_e32 v176, 16, v97
	v_and_b32_e32 v177, 0xffff0000, v97
	v_mul_f32_e32 v174, v183, v174
	v_mul_f32_e32 v175, v183, v175
	v_mul_f32_e32 v176, v183, v176
	v_mul_f32_e32 v177, v183, v177
	v_fma_f32 v64, v0, v174, v64
	v_fma_f32 v65, v1, v175, v65
	v_fma_f32 v66, v2, v176, v66
	v_fma_f32 v67, v3, v177, v67
	global_store_dwordx4 v166, v[64:67], s[36:37] offset:-4096
	v_mul_f32_e32 v185, v64, v64
	v_mul_f32_e32 v186, v65, v65
	v_mul_f32_e32 v187, v66, v66
	v_mul_f32_e32 v188, v67, v67
	s_waitcnt vmcnt(49)
	v_lshlrev_b32_e32 v174, 16, v98
	v_and_b32_e32 v175, 0xffff0000, v98
	v_lshlrev_b32_e32 v176, 16, v99
	v_and_b32_e32 v177, 0xffff0000, v99
	v_mul_f32_e32 v174, v183, v174
	v_mul_f32_e32 v175, v183, v175
	v_mul_f32_e32 v176, v183, v176
	v_mul_f32_e32 v177, v183, v177
	v_fma_f32 v68, v4, v174, v68
	v_fma_f32 v69, v5, v175, v69
	v_fma_f32 v70, v6, v176, v70
	v_fma_f32 v71, v7, v177, v71
	global_store_dwordx4 v166, v[68:71], s[36:37] offset:-3072
	v_fma_f32 v185, v68, v68, v185
	v_fma_f32 v186, v69, v69, v186
	v_fma_f32 v187, v70, v70, v187
	v_fma_f32 v188, v71, v71, v188
	s_waitcnt vmcnt(48)
	v_lshlrev_b32_e32 v174, 16, v100
	v_and_b32_e32 v175, 0xffff0000, v100
	v_lshlrev_b32_e32 v176, 16, v101
	v_and_b32_e32 v177, 0xffff0000, v101
	v_mul_f32_e32 v174, v183, v174
	v_mul_f32_e32 v175, v183, v175
	v_mul_f32_e32 v176, v183, v176
	v_mul_f32_e32 v177, v183, v177
	v_fma_f32 v72, v8, v174, v72
	v_fma_f32 v73, v9, v175, v73
	v_fma_f32 v74, v10, v176, v74
	v_fma_f32 v75, v11, v177, v75
	global_store_dwordx4 v166, v[72:75], s[36:37] offset:-2048
	v_fma_f32 v185, v72, v72, v185
	v_fma_f32 v186, v73, v73, v186
	v_fma_f32 v187, v74, v74, v187
	v_fma_f32 v188, v75, v75, v188
	s_waitcnt vmcnt(47)
; __device__ __forceinline__ unsigned pk2(float lo, float hi) { return pg8::cvt_pk_bf16(lo, hi); }
; __device__ __forceinline__ float bf_lo(unsigned w) { return __uint_as_float(w << 16); }
; __device__ __forceinline__ float bf_hi(unsigned w) { return __uint_as_float(w & 0xffff0000u); }
; #define P_IN INP(1)
; __global__ void __launch_bounds__(512, 2) fwd(Params P) {
;     ...
;             for (int j = 0; j < 8; ++j) { const f32x4 xv = __builtin_nontemporal_load(&xr[64 * j]); const u32x2 yw = __builtin_nontemporal_load(&yr[64 * j]); const f32x4 g = g1[64 * j];
;                 f32x4 t; t.x = xv.x + bf_lo(yw.x) * rsy * g.x; t.y = xv.y + bf_hi(yw.x) * rsy * g.y; t.z = xv.z + bf_lo(yw.y) * rsy * g.z; t.w = xv.w + bf_hi(yw.y) * rsy * g.w;
;                 v[j] = t; __builtin_nontemporal_store(t, &orow[64 * j]); s += (t.x * t.x + t.y * t.y) + (t.z * t.z + t.w * t.w); }
;             const float rs = __builtin_amdgcn_rsqf(wave_sum(s) * (1.f / DM) + EPS);
;             u32x2* o = (u32x2*)(XN + (size_t)m * DM) + lane;
; #pragma unroll
;             for (int j = 0; j < 8; ++j) { const f32x4 g = g2[64 * j]; u32x2 w; w.x = pk2(v[j].x * rs * g.x, v[j].y * rs * g.y); w.y = pk2(v[j].z * rs * g.z, v[j].w * rs * g.w); o[64 * j] = w; }
;             const f32x4 pv = ((const f32x4*)(P_IN + (size_t)m * PLE))[lane]; u32x2 pw; pw.x = pk2(pv.x, pv.y); pw.y = pk2(pv.z, pv.w);
;             ((u32x2*)(PB + (size_t)m * PLE))[lane] = pw;
	v_lshlrev_b32_e32 v174, 16, v102
	v_and_b32_e32 v175, 0xffff0000, v102
	v_lshlrev_b32_e32 v176, 16, v103
	v_and_b32_e32 v177, 0xffff0000, v103
	v_mul_f32_e32 v174, v183, v174
	v_mul_f32_e32 v175, v183, v175
	v_mul_f32_e32 v176, v183, v176
	v_mul_f32_e32 v177, v183, v177
	v_fma_f32 v76, v12, v174, v76
	v_fma_f32 v77, v13, v175, v77
	v_fma_f32 v78, v14, v176, v78
	v_fma_f32 v79, v15, v177, v79
	global_store_dwordx4 v166, v[76:79], s[36:37] offset:-1024
	v_fma_f32 v185, v76, v76, v185
	v_fma_f32 v186, v77, v77, v186
	v_fma_f32 v187, v78, v78, v187
	v_fma_f32 v188, v79, v79, v188
	s_waitcnt vmcnt(46)
	v_lshlrev_b32_e32 v174, 16, v104
	v_and_b32_e32 v175, 0xffff0000, v104
	v_lshlrev_b32_e32 v176, 16, v105
	v_and_b32_e32 v177, 0xffff0000, v105
	v_mul_f32_e32 v174, v183, v174
	v_mul_f32_e32 v175, v183, v175
	v_mul_f32_e32 v176, v183, v176
	v_mul_f32_e32 v177, v183, v177
	v_fma_f32 v80, v16, v174, v80
	v_fma_f32 v81, v17, v175, v81
	v_fma_f32 v82, v18, v176, v82
	v_fma_f32 v83, v19, v177, v83
	global_store_dwordx4 v166, v[80:83], s[36:37] offset:0
	v_fma_f32 v185, v80, v80, v185
	v_fma_f32 v186, v81, v81, v186
	v_fma_f32 v187, v82, v82, v187
	v_fma_f32 v188, v83, v83, v188
	s_waitcnt vmcnt(45)
	v_lshlrev_b32_e32 v174, 16, v106
	v_and_b32_e32 v175, 0xffff0000, v106
	v_lshlrev_b32_e32 v176, 16, v107
	v_and_b32_e32 v177, 0xffff0000, v107
	v_mul_f32_e32 v174, v183, v174
	v_mul_f32_e32 v175, v183, v175
	v_mul_f32_e32 v176, v183, v176
	v_mul_f32_e32 v177, v183, v177
	v_fma_f32 v84, v20, v174, v84
	v_fma_f32 v85, v21, v175, v85
	v_fma_f32 v86, v22, v176, v86
	v_fma_f32 v87, v23, v177, v87
	global_store_dwordx4 v166, v[84:87], s[36:37] offset:1024
	v_fma_f32 v185, v84, v84, v185
	v_fma_f32 v186, v85, v85, v186
	v_fma_f32 v187, v86, v86, v187
	v_fma_f32 v188, v87, v87, v188
	s_waitcnt vmcnt(44)
	v_lshlrev_b32_e32 v174, 16, v108
	v_and_b32_e32 v175, 0xffff0000, v108
	v_lshlrev_b32_e32 v176, 16, v109
	v_and_b32_e32 v177, 0xffff0000, v109
	v_mul_f32_e32 v174, v183, v174
	v_mul_f32_e32 v175, v183, v175
	v_mul_f32_e32 v176, v183, v176
	v_mul_f32_e32 v177, v183, v177
	v_fma_f32 v88, v24, v174, v88
	v_fma_f32 v89, v25, v175, v89
	v_fma_f32 v90, v26, v176, v90
	v_fma_f32 v91, v27, v177, v91
	global_store_dwordx4 v166, v[88:91], s[36:37] offset:2048
	v_fma_f32 v185, v88, v88, v185
	v_fma_f32 v186, v89, v89, v186
	v_fma_f32 v187, v90, v90, v187
	v_fma_f32 v188, v91, v91, v188
	s_waitcnt vmcnt(43)
	v_lshlrev_b32_e32 v174, 16, v110
	v_and_b32_e32 v175, 0xffff0000, v110
	v_lshlrev_b32_e32 v176, 16, v111
	v_and_b32_e32 v177, 0xffff0000, v111
	v_mul_f32_e32 v174, v183, v174
	v_mul_f32_e32 v175, v183, v175
	v_mul_f32_e32 v176, v183, v176
	v_mul_f32_e32 v177, v183, v177
	v_fma_f32 v92, v28, v174, v92
	v_fma_f32 v93, v29, v175, v93
	v_fma_f32 v94, v30, v176, v94
	v_fma_f32 v95, v31, v177, v95
	global_store_dwordx4 v166, v[92:95], s[36:37] offset:3072
	v_fma_f32 v185, v92, v92, v185
	v_fma_f32 v186, v93, v93, v186
	v_fma_f32 v187, v94, v94, v187
	v_fma_f32 v188, v95, v95, v188
	v_add_f32_e32 v185, v185, v186
	v_add_f32_e32 v187, v187, v188
	v_add_f32_e32 v185, v185, v187
	s_nop 1
	v_add_f32_dpp v185, v185, v185 quad_perm:[1,0,3,2] row_mask:0xf bank_mask:0xf
	s_nop 1
	v_add_f32_dpp v185, v185, v185 quad_perm:[2,3,0,1] row_mask:0xf bank_mask:0xf
	s_nop 1
	v_add_f32_dpp v185, v185, v185 row_half_mirror row_mask:0xf bank_mask:0xf
	s_nop 1
	v_add_f32_dpp v185, v185, v185 row_mirror row_mask:0xf bank_mask:0xf
	s_nop 1
	v_readlane_b32 s24, v185, 0
	v_readlane_b32 s25, v185, 16
	v_readlane_b32 s26, v185, 32
	v_readlane_b32 s27, v185, 48
	v_mov_b32_e32 v184, s24
	v_add_f32_e32 v184, s25, v184
	v_add_f32_e32 v184, s26, v184
	v_add_f32_e32 v184, s27, v184
	v_fmamk_f32 v184, v184, 0x3a000000, v182
	v_rsq_f32_e32 v184, v184
	s_nop 0
	v_mul_f32_e32 v174, v184, v64
	v_mul_f32_e32 v175, v184, v65
	v_mul_f32_e32 v176, v184, v66
	v_mul_f32_e32 v177, v184, v67
	v_mul_f32_e32 v174, v174, v32
	v_mul_f32_e32 v175, v175, v33
	v_mul_f32_e32 v176, v176, v34
	v_mul_f32_e32 v177, v177, v35
	v_cvt_pk_bf16_f32 v96, v174, v175
	v_cvt_pk_bf16_f32 v97, v176, v177
	global_store_dwordx2 v181, v[96:97], s[38:39] offset:0
	v_mul_f32_e32 v174, v184, v68
	v_mul_f32_e32 v175, v184, v69
	v_mul_f32_e32 v176, v184, v70
	v_mul_f32_e32 v177, v184, v71
	v_mul_f32_e32 v174, v174, v36
	v_mul_f32_e32 v175, v175, v37
	v_mul_f32_e32 v176, v176, v38
	v_mul_f32_e32 v177, v177, v39
	v_cvt_pk_bf16_f32 v98, v174, v175
	v_cvt_pk_bf16_f32 v99, v176, v177
	global_store_dwordx2 v181, v[98:99], s[38:39] offset:512
	v_mul_f32_e32 v174, v184, v72
	v_mul_f32_e32 v175, v184, v73
	v_mul_f32_e32 v176, v184, v74
	v_mul_f32_e32 v177, v184, v75
	v_mul_f32_e32 v174, v174, v40
	v_mul_f32_e32 v175, v175, v41
	v_mul_f32_e32 v176, v176, v42
	v_mul_f32_e32 v177, v177, v43
	v_cvt_pk_bf16_f32 v100, v174, v175
	v_cvt_pk_bf16_f32 v101, v176, v177
	global_store_dwordx2 v181, v[100:101], s[38:39] offset:1024
	v_mul_f32_e32 v174, v184, v76
	v_mul_f32_e32 v175, v184, v77
	v_mul_f32_e32 v176, v184, v78
	v_mul_f32_e32 v177, v184, v79
	v_mul_f32_e32 v174, v174, v44
	v_mul_f32_e32 v175, v175, v45
	v_mul_f32_e32 v176, v176, v46
	v_mul_f32_e32 v177, v177, v47
	v_cvt_pk_bf16_f32 v102, v174, v175
	v_cvt_pk_bf16_f32 v103, v176, v177
	global_store_dwordx2 v181, v[102:103], s[38:39] offset:1536
	v_mul_f32_e32 v174, v184, v80
	v_mul_f32_e32 v175, v184, v81
	v_mul_f32_e32 v176, v184, v82
	v_mul_f32_e32 v177, v184, v83
	v_mul_f32_e32 v174, v174, v48
	v_mul_f32_e32 v175, v175, v49
	v_mul_f32_e32 v176, v176, v50
	v_mul_f32_e32 v177, v177, v51
	v_cvt_pk_bf16_f32 v104, v174, v175
	v_cvt_pk_bf16_f32 v105, v176, v177
	global_store_dwordx2 v181, v[104:105], s[38:39] offset:2048
	v_mul_f32_e32 v174, v184, v84
	v_mul_f32_e32 v175, v184, v85
	v_mul_f32_e32 v176, v184, v86
	v_mul_f32_e32 v177, v184, v87
	v_mul_f32_e32 v174, v174, v52
	v_mul_f32_e32 v175, v175, v53
	v_mul_f32_e32 v176, v176, v54
	v_mul_f32_e32 v177, v177, v55
	v_cvt_pk_bf16_f32 v106, v174, v175
	v_cvt_pk_bf16_f32 v107, v176, v177
	global_store_dwordx2 v181, v[106:107], s[38:39] offset:2560
	v_mul_f32_e32 v174, v184, v88
	v_mul_f32_e32 v175, v184, v89
	v_mul_f32_e32 v176, v184, v90
	v_mul_f32_e32 v177, v184, v91
	v_mul_f32_e32 v174, v174, v56
	v_mul_f32_e32 v175, v175, v57
	v_mul_f32_e32 v176, v176, v58
	v_mul_f32_e32 v177, v177, v59
	v_cvt_pk_bf16_f32 v108, v174, v175
	v_cvt_pk_bf16_f32 v109, v176, v177
	global_store_dwordx2 v181, v[108:109], s[38:39] offset:3072
	v_mul_f32_e32 v174, v184, v92
	v_mul_f32_e32 v175, v184, v93
	v_mul_f32_e32 v176, v184, v94
	v_mul_f32_e32 v177, v184, v95
	v_mul_f32_e32 v174, v174, v60
	v_mul_f32_e32 v175, v175, v61
	v_mul_f32_e32 v176, v176, v62
	v_mul_f32_e32 v177, v177, v63
	v_cvt_pk_bf16_f32 v110, v174, v175
	v_cvt_pk_bf16_f32 v111, v176, v177
	global_store_dwordx2 v181, v[110:111], s[38:39] offset:3584
	s_waitcnt vmcnt(51)
	v_cvt_pk_bf16_f32 v114, v114, v115
	v_cvt_pk_bf16_f32 v115, v116, v117
	global_store_dwordx2 v181, v[114:115], s[40:41]
	s_add_i32 s30, s30, s82
	s_cmpk_gt_i32 s30, 0x7fff
	s_cbranch_scc1 .Lp5b_done
	s_branch .Lp5b_loop
